# m5: next work-unit index claimed at the start of each small unit (atomic latency hidden); chunk-boundary decay load issued before the state MFMAs instead of after
# baseline (speedup 1.0000x reference)
; PH_FN ph_m5(const Params& prm, unsigned char* lds, int l_, int* s_unit) {
;     const Ctx C = make_ctx(prm.ws, lds, l_);
;     unsigned* qctr = WSP(unsigned, WS_CTL) + 64 * (C.l + 1);
;     bf16_t* Yb = WSP(bf16_t, WS_Y);
;     for (;;) {
;         __syncthreads();
;         if (C.tid == 0) *s_unit = (int)atomicAdd(qctr, 1u);
;         __syncthreads();
;         int idx = *s_unit; idx = __builtin_amdgcn_readfirstlane(idx);
;         if (idx >= 2048) break;
.LBB0_641:
	s_or_b64 exec, exec, s[0:1]
	v_mov_b32_e32 v178, v194
	s_mov_b32 s0, s38
	s_mov_b32 s1, s36
	s_mov_b32 s2, s69
	s_waitcnt lgkmcnt(0)
	s_barrier
	s_lshl_b32 s0, s2, 6
	s_ashr_i32 s1, s0, 31
	s_mov_b64 s[92:93], s[66:67]
	s_lshl_b64 s[0:1], s[0:1], 2
	s_add_u32 s46, s92, s0
	s_addc_u32 s47, s93, s1
	s_add_u32 s40, s92, 0x34964000
	s_addc_u32 s49, s93, 0
	s_add_u32 s0, s92, 0x7964000
	v_writelane_b32 v255, s0, 21
	s_addc_u32 s0, s93, 0
	v_writelane_b32 v255, s0, 22
	s_add_u32 s0, s92, 0x1964000
	v_writelane_b32 v255, s0, 23
	s_addc_u32 s0, s93, 0
	v_writelane_b32 v255, s0, 24
	s_add_u32 s0, s92, 0x10000
	v_writelane_b32 v255, s0, 25
	s_addc_u32 s0, s93, 0
	v_writelane_b32 v255, s0, 26
	s_add_u32 s0, s92, 0x29964000
	v_writelane_b32 v255, s0, 27
	s_addc_u32 s0, s93, 0
	v_writelane_b32 v255, s0, 28
	s_add_u32 s0, s92, 0x9964000
	v_writelane_b32 v255, s0, 29
	s_addc_u32 s0, s93, 0
	v_writelane_b32 v255, s0, 30
	s_add_u32 s0, s92, 0x3964000
	v_writelane_b32 v255, s0, 31
	s_addc_u32 s0, s93, 0
	v_writelane_b32 v255, s0, 32
	s_add_u32 s0, s92, 0x110000
	v_writelane_b32 v255, s0, 33
	s_addc_u32 s0, s93, 0
	v_writelane_b32 v255, s0, 34
	s_add_u32 s0, s92, 0x38964000
	v_writelane_b32 v255, s0, 35
	s_addc_u32 s0, s93, 0
	v_writelane_b32 v255, s0, 36
	s_add_u32 s0, s92, 0x25964000
	v_writelane_b32 v255, s0, 37
	s_addc_u32 s0, s93, 0
	v_writelane_b32 v255, s0, 38
	s_add_u32 s0, s92, 0x2c964000
	v_writelane_b32 v255, s0, 39
	s_addc_u32 s0, s93, 0
	v_writelane_b32 v255, s0, 40
	s_add_u32 s0, s92, 0x2f964000
	v_writelane_b32 v255, s0, 41
	s_addc_u32 s0, s93, 0
	v_writelane_b32 v255, s0, 42
	s_add_u32 s0, s92, 0x32964000
	v_writelane_b32 v255, s0, 43
	s_addc_u32 s0, s93, 0
	v_writelane_b32 v255, s0, 44
	s_add_u32 s0, s92, 0x36964000
	v_writelane_b32 v255, s0, 45
	s_addc_u32 s0, s93, 0
	v_writelane_b32 v255, s0, 46
	s_add_u32 s0, s92, 0x1966000
	v_writelane_b32 v255, s0, 47
	s_addc_u32 s0, s93, 0
	v_writelane_b32 v255, s0, 48
	s_add_u32 s0, s92, 0x10100
	v_writelane_b32 v255, s0, 49
	s_addc_u32 s0, s93, 0
	v_cmp_eq_u32_e64 s[28:29], 0, v178
	v_writelane_b32 v255, s0, 50
	s_mov_b32 s32, 0
	s_branch .LBB0_645

; PH_FN ph_m5(const Params& prm, unsigned char* lds, int l_, int* s_unit) {
;     ...
;     for (;;) {
;         __syncthreads();
;         if (C.tid == 0) *s_unit = (int)atomicAdd(qctr, 1u);
;         __syncthreads();
;         int idx = *s_unit; idx = __builtin_amdgcn_readfirstlane(idx);
;         if (idx >= 2048) break;
.LBB0_645:
	s_barrier
	s_and_saveexec_b64 s[0:1], s[28:29]
	s_cbranch_execz .LBB0_649
	s_mov_b64 s[6:7], exec
	v_mbcnt_lo_u32_b32 v0, s6, 0
	v_mbcnt_hi_u32_b32 v0, s7, v0
	v_cmp_eq_u32_e32 vcc, 0, v0
	s_and_saveexec_b64 s[2:3], vcc
	s_cbranch_execz .LBB0_648
	s_bcnt1_i32_b64 s6, s[6:7]
	v_mov_b32_e32 v2, s6
	s_cmp_eq_u32 s32, 1
	s_cbranch_scc1 .Lm5_havepf
	global_atomic_add v244, v1, v197, s[46:47] offset:256 sc0
.Lm5_havepf:
	s_waitcnt vmcnt(0)
	v_mov_b32_e32 v2, v244

; PH_FN ph_m5(const Params& prm, unsigned char* lds, int l_, int* s_unit) {
;     ...
;         __syncthreads();
;         if (C.tid == 0) *s_unit = (int)atomicAdd(qctr, 1u);
;         __syncthreads();
;         int idx = *s_unit; idx = __builtin_amdgcn_readfirstlane(idx);
;         if (idx >= 2048) break;
;         int tid = C.tid; asm volatile("" : "+v"(tid));
;         if (idx < 512) {
;             const int qb = 15 - (idx >> 5), rem = idx & 31;
;             const int b = rem >> 3, h = rem & 7; const size_t bh = (size_t)(b * 8 + h);
;             const bf16_t* QH = WSP(bf16_t, WS_R2); const bf16_t* KH = QH + (size_t)T * 8 * 192; const bf16_t* VTM = KH + (size_t)T * 8 * 192;
;             attn_unit<192, 128, 0, 128>(tid, lds, QH + bh * SEQ * 192, 192, KH + bh * SEQ * 192, 192, VTM + bh * 128 * SEQ, nullptr, 0.07216878364870322f * LOG2E,
;                                    Yb + (size_t)T * 1024 + (size_t)b * SEQ * 1024 + h * 128, 1024, qb, nullptr, 0);
;         } else if (idx < 1024) {
;             const int qb = (idx - 512) >> 5, r2 = idx & 31, b = r2 >> 3, h = (r2 & 7) >> 1, half = r2 & 1;
;             const bf16_t* PROJ = WSP(bf16_t, WS_BIG); const bf16_t* VTR = WSP(bf16_t, WS_WA) + (size_t)T * 1024;
;             attn_unit<256, 128, 1, 256>(tid, lds, PROJ + (size_t)b * SEQ * LDP + RQ0 + h * 256, LDP, PROJ + (size_t)b * SEQ * LDP + RK0 + h * 256, LDP,
;                                    VTR + (size_t)(b * 4 + h) * 256 * SEQ, WSP(float, WS_A2R) + h * SEQ, 0.f,
;                                    Yb + (size_t)2 * T * 1024 + (size_t)b * SEQ * 1024 + h * 256 + half * 128, 1024, qb,
;                                    WSP(float, WS_R1) + ((size_t)((b * 16 + qb) * 4 + h) * 256 + half * 128) * 256, half * 128);
;         } else {
;             const int qb = (idx - 1024) >> 6, r3 = idx & 63, b = r3 >> 4, h = r3 & 15, gq = h >> 3;
;             const bf16_t* BC = WSP(bf16_t, WS_H) + (size_t)T * 1024; const bf16_t* XT = WSP(bf16_t, WS_WA);
;             attn_unit<128, 64, 1, 64>(tid, lds, BC + (size_t)b * SEQ * 512 + 256 + gq * 128, 512, BC + (size_t)b * SEQ * 512 + gq * 128, 512,
;                                   XT + (size_t)(b * 16 + h) * 64 * SEQ, WSP(float, WS_A2S) + (size_t)(b * 16 + h) * SEQ, 0.f,
;                                   Yb + (size_t)b * SEQ * 1024 + h * 64, 1024, qb,
.LBB0_649:
	s_or_b64 exec, exec, s[0:1]
	s_waitcnt lgkmcnt(0)
	s_barrier
	ds_read_b32 v0, v1 offset:8
	s_mov_b64 s[0:1], -1
	s_waitcnt lgkmcnt(0)
	v_readfirstlane_b32 s96, v0
	s_cmpk_gt_i32 s96, 0x7ff
	s_cbranch_scc1 .LBB0_644
	s_mov_b32 s32, 0
	s_cmpk_lt_i32 s96, 0x200
	s_cbranch_scc1 .Lm5_nopf
	s_mov_b32 s32, 1
	s_and_saveexec_b64 s[98:99], s[28:29]
	s_cbranch_execz .Lm5_pfskip
	global_atomic_add v244, v1, v197, s[46:47] offset:256 sc0
.Lm5_pfskip:
	s_or_b64 exec, exec, s[98:99]
.Lm5_nopf:
	v_mov_b32_e32 v179, v178
	s_cmpk_gt_i32 s96, 0x1ff
	s_cbranch_scc0 .LBB0_697
	s_cmpk_gt_u32 s96, 0x3ff
	s_cbranch_scc0 .LBB0_685
	s_add_i32 s14, s96, 0xfffffc00
	s_bfe_u32 s13, s96, 0x20004
	s_lshr_b32 s12, s14, 6
	s_lshl_b32 s0, s13, 22
	v_readlane_b32 s1, v255, 21
	s_add_u32 s0, s1, s0
	v_readlane_b32 s1, v255, 22
	s_addc_u32 s1, s1, 0
	s_lshl_b32 s2, s96, 5
	s_and_b32 s2, s2, 0x100
	s_add_u32 s0, s0, s2
	s_addc_u32 s1, s1, 0
	s_and_b32 s2, s96, 63
	s_lshl_b32 s11, s2, 19
	s_lshl_b32 s10, s2, 14
	v_readlane_b32 s2, v255, 25
	s_add_u32 s2, s2, s10
	v_readlane_b32 s3, v255, 26
	v_readfirstlane_b32 s4, v179
	s_addc_u32 s3, s3, 0
	s_ashr_i32 s17, s4, 6
	s_lshl_b32 s86, s12, 8
	s_lshl_b32 s16, s17, 5
	v_and_b32_e32 v34, 31, v179
	s_add_i32 s16, s16, s86
	v_or_b32_e32 v98, s16, v34
	v_ashrrev_i32_e32 v99, 31, v98
	v_bfe_u32 v35, v179, 5, 1
	v_lshlrev_b64 v[2:3], 10, v[98:99]
	v_lshl_add_u64 v[2:3], s[0:1], 0, v[2:3]
	v_lshlrev_b32_e32 v100, 4, v35
	v_mov_b32_e32 v101, v1
	v_lshl_add_u64 v[2:3], v[2:3], 0, v[100:101]
	global_load_dwordx4 v[74:77], v[2:3], off offset:512
	global_load_dwordx4 v[78:81], v[2:3], off offset:544
	global_load_dwordx4 v[70:73], v[2:3], off offset:576
	global_load_dwordx4 v[66:69], v[2:3], off offset:608
	global_load_dwordx4 v[62:65], v[2:3], off offset:640
	global_load_dwordx4 v[58:61], v[2:3], off offset:672
	global_load_dwordx4 v[54:57], v[2:3], off offset:704
	global_load_dwordx4 v[50:53], v[2:3], off offset:736
	v_lshl_add_u64 v[2:3], v[98:99], 2, s[2:3]
	v_mov_b32_e32 v0, v179
	global_load_dword v99, v[2:3], off
	s_nop 0
	v_ashrrev_i32_e32 v2, 31, v0
	v_lshrrev_b32_e32 v3, 28, v2
	v_add_u32_e32 v3, v0, v3
	v_ashrrev_i32_e32 v4, 4, v3
	v_add_u32_e32 v4, s86, v4
	v_and_b32_e32 v3, 0x1ffffff0, v3
	v_ashrrev_i32_e32 v5, 31, v4
	v_sub_u32_e32 v3, v0, v3
	v_lshlrev_b64 v[4:5], 10, v[4:5]
	v_lshlrev_b32_e32 v6, 3, v3
	v_lshl_add_u64 v[4:5], s[0:1], 0, v[4:5]
	v_ashrrev_i32_e32 v7, 31, v6
	v_add_u32_e32 v3, 0x200, v0
	v_lshl_add_u64 v[4:5], v[6:7], 1, v[4:5]
	v_ashrrev_i32_e32 v6, 31, v3
	v_lshrrev_b32_e32 v6, 28, v6
	v_add_u32_e32 v8, v3, v6
	v_ashrrev_i32_e32 v6, 4, v8
	v_add_u32_e32 v6, s86, v6
	v_and_b32_e32 v8, 0x1ffffff0, v8
	v_ashrrev_i32_e32 v7, 31, v6
	v_sub_u32_e32 v3, v3, v8
	v_lshlrev_b64 v[6:7], 10, v[6:7]
	v_lshlrev_b32_e32 v8, 3, v3
	v_lshl_add_u64 v[6:7], s[0:1], 0, v[6:7]
	v_ashrrev_i32_e32 v9, 31, v8
	v_lshl_add_u64 v[6:7], v[8:9], 1, v[6:7]
	global_load_dwordx4 v[82:85], v[4:5], off
	global_load_dwordx4 v[86:89], v[6:7], off
	v_cmp_gt_i32_e32 vcc, s41, v0
	s_and_saveexec_b64 s[6:7], vcc
	s_cbranch_execz .LBB0_654
	v_lshrrev_b32_e32 v2, 26, v2
	v_add_u32_e32 v2, v0, v2
	v_and_b32_e32 v2, 0xffffffc0, v2
	v_sub_u32_e32 v0, v0, v2
	v_lshrrev_b16_sdwa v3, v230, sext(v0) dst_sel:DWORD dst_unused:UNUSED_PAD src0_sel:DWORD src1_sel:BYTE_0
	v_and_b32_e32 v3, 31, v3
	v_add_u16_e32 v3, v0, v3
	v_ashrrev_i16_sdwa v4, v231, sext(v3) dst_sel:DWORD dst_unused:UNUSED_PAD src0_sel:DWORD src1_sel:BYTE_0
	v_and_b32_e32 v3, 0xe0, v3
	v_sub_u16_e32 v0, v0, v3
	v_lshlrev_b32_sdwa v0, v197, sext(v0) dst_sel:DWORD dst_unused:UNUSED_PAD src0_sel:DWORD src1_sel:BYTE_0
	v_readlane_b32 s4, v255, 23
	v_add_u16_e32 v0, v0, v4
	s_add_u32 s4, s4, s11
	v_readlane_b32 s5, v255, 24
	v_lshlrev_b32_e32 v5, 5, v4
	v_ashrrev_i16_e32 v0, 1, v0
	s_addc_u32 s5, s5, 0
	s_lshl_b32 s8, s12, 15
	v_and_or_b32 v2, v5, 32, v2
	v_bfe_i32 v0, v0, 0, 16
	s_add_u32 s8, s4, s8
	v_add_lshl_u32 v2, v2, v0, 3
	s_addc_u32 s9, s5, 0
	v_ashrrev_i32_e32 v3, 31, v2
	v_lshl_add_u64 v[2:3], v[2:3], 1, s[8:9]
	global_load_dwordx4 v[90:93], v[2:3], off

; __device__ __forceinline__ unsigned pk2(float lo, float hi) { f32x2 v = {lo, hi}; bf16x2_t b = __builtin_convertvector(v, bf16x2_t); return __builtin_bit_cast(unsigned, b); }
; __device__ __forceinline__ float ex2(float x) { return __builtin_amdgcn_exp2f(x); }
; #define MFMA32(a, b, c) __builtin_amdgcn_mfma_f32_32x32x16_bf16((a), (b), (c), 0, 0, 0)
; template <int DQK, int DV, int MODE, int VR> ...
;     ...
;     if (MODE == 1 && qb > 0) {
;         constexpr int SSTR = DQK * 2 + 16, SP_OFF = STG, NLD = DV * DQK / 4 / 512;
;         static_assert(SP_OFF + DV * SSTR <= 147456, "Sprev staging");
; #pragma unroll 4
;         for (int i = 0; i < NLD; ++i) { const int idx = tid + 512 * i, e = idx / (DQK / 4), c4 = idx % (DQK / 4);
;             const f32x4 v = *(const f32x4*)(Sprev + (size_t)e * DQK + 4 * c4);
;             u32x2 w; w.x = pk2(v[0], v[1]); w.y = pk2(v[2], v[3]);
;             *(u32x2*)(lds + SP_OFF + e * SSTR + c4 * 8) = w; }
;         __syncthreads();
; #pragma unroll
;         for (int b = 0; b < NBLK; ++b)
; #pragma unroll
;             for (int ks = 0; ks < NKS; ++ks) { const bf16x8 a = *(const bf16x8*)(lds + SP_OFF + (32 * b + r32) * SSTR + (16 * ks + 8 * hi) * 2); o[b] = MFMA32(a, qf[ks], o[b]); }
;         const float dq = ex2(a2t - a2[qb * 256 - 1]);
; #pragma unroll
;         for (int b = 0; b < NBLK; ++b)
; #pragma unroll
;             for (int r = 0; r < 16; ++r) o[b][r] *= dq;
.LBB0_658:
	s_lshl_b32 s4, s13, 8
	s_lshl_b32 s5, s12, 4
	v_ashrrev_i32_e32 v0, 31, v179
	s_add_i32 s4, s4, s5
	v_lshrrev_b32_e32 v0, 27, v0
	s_or_b32 s8, s4, s18
	s_mov_b32 s9, s87
	v_add_u32_e32 v0, v179, v0
	s_lshl_b64 s[8:9], s[8:9], 15
	v_readlane_b32 s4, v255, 27
	v_ashrrev_i32_e32 v6, 5, v0
	v_and_b32_e32 v0, 0xffffffe0, v0
	s_add_u32 s8, s4, s8
	v_readlane_b32 s4, v255, 28
	v_sub_u32_e32 v0, v179, v0
	v_ashrrev_i32_e32 v7, 31, v6
	s_addc_u32 s9, s4, s9
	v_lshlrev_b64 v[2:3], 9, v[6:7]
	v_lshlrev_b32_e32 v4, 2, v0
	v_lshl_add_u64 v[2:3], s[8:9], 0, v[2:3]
	v_ashrrev_i32_e32 v5, 31, v4
	v_lshl_add_u64 v[2:3], v[4:5], 2, v[2:3]
	global_load_dwordx4 v[120:123], v[2:3], off
	v_lshlrev_b32_e32 v0, 3, v0
	v_mul_lo_u32 v4, v6, s97
	v_add3_u32 v136, 16, v4, v0
	v_add_u32_e32 v0, 0x200, v179
	v_ashrrev_i32_e32 v2, 31, v0
	v_lshrrev_b32_e32 v2, 27, v2
	v_add_u32_e32 v2, v0, v2
	v_ashrrev_i32_e32 v6, 5, v2
	v_and_b32_e32 v2, 0xffffffe0, v2
	v_sub_u32_e32 v0, v0, v2
	v_ashrrev_i32_e32 v7, 31, v6
	v_lshlrev_b64 v[2:3], 9, v[6:7]
	v_lshlrev_b32_e32 v4, 2, v0
	v_lshl_add_u64 v[2:3], s[8:9], 0, v[2:3]
	v_ashrrev_i32_e32 v5, 31, v4
	v_lshl_add_u64 v[2:3], v[4:5], 2, v[2:3]
	global_load_dwordx4 v[124:127], v[2:3], off
	v_lshlrev_b32_e32 v0, 3, v0
	v_mul_lo_u32 v4, v6, s97
	v_add3_u32 v137, 16, v4, v0
	v_add_u32_e32 v0, 0x400, v179
	v_ashrrev_i32_e32 v2, 31, v0
	v_lshrrev_b32_e32 v2, 27, v2
	v_add_u32_e32 v2, v0, v2
	v_ashrrev_i32_e32 v6, 5, v2
	v_and_b32_e32 v2, 0xffffffe0, v2
	v_sub_u32_e32 v0, v0, v2
	v_ashrrev_i32_e32 v7, 31, v6
	v_lshlrev_b64 v[2:3], 9, v[6:7]
	v_lshlrev_b32_e32 v4, 2, v0
	v_lshl_add_u64 v[2:3], s[8:9], 0, v[2:3]
	v_ashrrev_i32_e32 v5, 31, v4
	v_lshl_add_u64 v[2:3], v[4:5], 2, v[2:3]
	global_load_dwordx4 v[128:131], v[2:3], off
	v_lshlrev_b32_e32 v0, 3, v0
	v_mul_lo_u32 v4, v6, s97
	v_add3_u32 v138, 16, v4, v0
	v_add_u32_e32 v0, 0x600, v179
	v_ashrrev_i32_e32 v2, 31, v0
	v_lshrrev_b32_e32 v2, 27, v2
	v_add_u32_e32 v2, v0, v2
	v_ashrrev_i32_e32 v6, 5, v2
	v_and_b32_e32 v2, 0xffffffe0, v2
	v_sub_u32_e32 v0, v0, v2
	v_ashrrev_i32_e32 v7, 31, v6
	v_lshlrev_b64 v[2:3], 9, v[6:7]
	v_lshlrev_b32_e32 v4, 2, v0
	v_lshl_add_u64 v[2:3], s[8:9], 0, v[2:3]
	v_ashrrev_i32_e32 v5, 31, v4
	v_lshl_add_u64 v[2:3], v[4:5], 2, v[2:3]
	global_load_dwordx4 v[132:135], v[2:3], off
	v_lshlrev_b32_e32 v0, 3, v0
	s_lshl_b64 s[8:9], s[86:87], 2
	s_add_u32 s2, s2, s8
	s_addc_u32 s3, s3, s9
	global_load_dword v245, v1, s[2:3] offset:-4
	v_mul_lo_u32 v4, v6, s97
	v_add3_u32 v139, 16, v4, v0
	s_waitcnt vmcnt(0)
	v_cvt_pk_bf16_f32 v120, v120, v121
	v_cvt_pk_bf16_f32 v121, v122, v123
	ds_write_b64 v136, v[120:121] offset:26880
	v_cvt_pk_bf16_f32 v124, v124, v125
	v_cvt_pk_bf16_f32 v125, v126, v127
	ds_write_b64 v137, v[124:125] offset:26880
	v_cvt_pk_bf16_f32 v128, v128, v129
	v_cvt_pk_bf16_f32 v129, v130, v131
	ds_write_b64 v138, v[128:129] offset:26880
	v_cvt_pk_bf16_f32 v132, v132, v133
	v_cvt_pk_bf16_f32 v133, v134, v135
	ds_write_b64 v139, v[132:133] offset:26880
	v_mul_u32_u24_e32 v0, 0x110, v34
	v_add3_u32 v0, 16, v100, v0
	s_waitcnt lgkmcnt(0)
	s_barrier
	ds_read_b128 v[2:5], v0 offset:26880
	ds_read_b128 v[18:21], v0 offset:26912
	s_waitcnt lgkmcnt(1)
	v_mfma_f32_32x32x16_bf16 v[2:17], v[2:5], v[74:77], 0
	ds_read_b128 v[36:39], v0 offset:35616
	s_waitcnt lgkmcnt(1)
	v_mfma_f32_32x32x16_bf16 v[2:17], v[18:21], v[78:81], v[2:17]
	ds_read_b128 v[212:215], v0 offset:26944
	ds_read_b128 v[216:219], v0 offset:26976
	ds_read_b128 v[220:223], v0 offset:27008
	s_waitcnt lgkmcnt(2)
	v_mfma_f32_32x32x16_bf16 v[2:17], v[212:215], v[70:73], v[2:17]
	ds_read_b128 v[212:215], v0 offset:27040
	s_waitcnt lgkmcnt(2)
	v_mfma_f32_32x32x16_bf16 v[2:17], v[216:219], v[66:69], v[2:17]
	ds_read_b128 v[216:219], v0 offset:27072
	s_waitcnt lgkmcnt(2)
	v_mfma_f32_32x32x16_bf16 v[2:17], v[220:223], v[62:65], v[2:17]
	ds_read_b128 v[220:223], v0 offset:27104
	s_waitcnt lgkmcnt(2)
	v_mfma_f32_32x32x16_bf16 v[2:17], v[212:215], v[58:61], v[2:17]
	ds_read_b128 v[212:215], v0 offset:35584
	s_waitcnt lgkmcnt(2)
	v_mfma_f32_32x32x16_bf16 v[2:17], v[216:219], v[54:57], v[2:17]
	s_waitcnt lgkmcnt(1)
	v_mfma_f32_32x32x16_bf16 v[2:17], v[220:223], v[50:53], v[2:17]
	s_waitcnt lgkmcnt(0)
	v_mfma_f32_32x32x16_bf16 v[18:33], v[212:215], v[74:77], 0
	v_mfma_f32_32x32x16_bf16 v[18:33], v[36:39], v[78:81], v[18:33]
	ds_read_b128 v[212:215], v0 offset:35648
	ds_read_b128 v[216:219], v0 offset:35680
	ds_read_b128 v[220:223], v0 offset:35712
	s_waitcnt lgkmcnt(2)
	v_mfma_f32_32x32x16_bf16 v[18:33], v[212:215], v[70:73], v[18:33]
	ds_read_b128 v[212:215], v0 offset:35744
	s_waitcnt lgkmcnt(2)
	v_mfma_f32_32x32x16_bf16 v[18:33], v[216:219], v[66:69], v[18:33]
	ds_read_b128 v[216:219], v0 offset:35776
	s_waitcnt lgkmcnt(2)
	v_mfma_f32_32x32x16_bf16 v[18:33], v[220:223], v[62:65], v[18:33]
	ds_read_b128 v[220:223], v0 offset:35808
	s_waitcnt lgkmcnt(2)
	v_mfma_f32_32x32x16_bf16 v[18:33], v[212:215], v[58:61], v[18:33]
	s_waitcnt lgkmcnt(1)
	v_mfma_f32_32x32x16_bf16 v[18:33], v[216:219], v[54:57], v[18:33]
	v_sub_f32_e32 v0, v99, v245
	s_waitcnt lgkmcnt(0)
	v_mfma_f32_32x32x16_bf16 v[18:33], v[220:223], v[50:53], v[18:33]
	v_exp_f32_e32 v0, v0
	s_nop 0
	v_pk_mul_f32 v[16:17], v[16:17], v[0:1] op_sel_hi:[1,0]
	v_pk_mul_f32 v[14:15], v[14:15], v[0:1] op_sel_hi:[1,0]
	v_pk_mul_f32 v[12:13], v[12:13], v[0:1] op_sel_hi:[1,0]
	v_pk_mul_f32 v[10:11], v[10:11], v[0:1] op_sel_hi:[1,0]
	v_pk_mul_f32 v[8:9], v[8:9], v[0:1] op_sel_hi:[1,0]
	v_pk_mul_f32 v[6:7], v[6:7], v[0:1] op_sel_hi:[1,0]
	v_pk_mul_f32 v[4:5], v[4:5], v[0:1] op_sel_hi:[1,0]
	v_pk_mul_f32 v[2:3], v[2:3], v[0:1] op_sel_hi:[1,0]
	s_nop 1
	v_pk_mul_f32 v[32:33], v[32:33], v[0:1] op_sel_hi:[1,0]
	v_pk_mul_f32 v[30:31], v[30:31], v[0:1] op_sel_hi:[1,0]
	v_pk_mul_f32 v[28:29], v[28:29], v[0:1] op_sel_hi:[1,0]
	v_pk_mul_f32 v[26:27], v[26:27], v[0:1] op_sel_hi:[1,0]
	v_pk_mul_f32 v[24:25], v[24:25], v[0:1] op_sel_hi:[1,0]
	v_pk_mul_f32 v[22:23], v[22:23], v[0:1] op_sel_hi:[1,0]
	v_pk_mul_f32 v[20:21], v[20:21], v[0:1] op_sel_hi:[1,0]
	v_pk_mul_f32 v[18:19], v[18:19], v[0:1] op_sel_hi:[1,0]

; __device__ __forceinline__ unsigned pk2(float lo, float hi) { f32x2 v = {lo, hi}; bf16x2_t b = __builtin_convertvector(v, bf16x2_t); return __builtin_bit_cast(unsigned, b); }
; template <int DQK, int DV, int MODE, int VR> ...
;     ...
;         constexpr int SSTR = DQK * 2 + 16, SP_OFF = STG, NLD = DV * DQK / 4 / 512;
;         static_assert(SP_OFF + DV * SSTR <= 147456, "Sprev staging");
; #pragma unroll 4
;         for (int i = 0; i < NLD; ++i) { const int idx = tid + 512 * i, e = idx / (DQK / 4), c4 = idx % (DQK / 4);
;             const f32x4 v = *(const f32x4*)(Sprev + (size_t)e * DQK + 4 * c4);
;             u32x2 w; w.x = pk2(v[0], v[1]); w.y = pk2(v[2], v[3]);
;             *(u32x2*)(lds + SP_OFF + e * SSTR + c4 * 8) = w; }
;         __syncthreads();
.LBB0_694:
	v_add_u32_e32 v8, s11, v179
	v_mov_b32_e32 v2, v8
	v_ashrrev_i32_e32 v3, 31, v2
	v_lshrrev_b32_e32 v3, 26, v3
	v_add_u32_e32 v3, v2, v3
	v_ashrrev_i32_e32 v6, 6, v3
	v_and_b32_e32 v3, 0xffffffc0, v3
	v_sub_u32_e32 v9, v2, v3
	v_ashrrev_i32_e32 v7, 31, v6
	v_lshlrev_b64 v[2:3], 10, v[6:7]
	v_lshlrev_b32_e32 v4, 2, v9
	v_lshl_add_u64 v[2:3], s[2:3], 0, v[2:3]
	v_ashrrev_i32_e32 v5, 31, v4
	v_lshl_add_u64 v[2:3], v[4:5], 2, v[2:3]
	global_load_dwordx4 v[182:185], v[2:3], off
	v_mul_lo_u32 v4, v6, s94
	v_lshlrev_b32_e32 v5, 3, v9
	v_add3_u32 v74, 16, v4, v5
	v_add_u32_e32 v2, 0x200, v8
	v_ashrrev_i32_e32 v3, 31, v2
	v_lshrrev_b32_e32 v3, 26, v3
	v_add_u32_e32 v3, v2, v3
	v_ashrrev_i32_e32 v6, 6, v3
	v_and_b32_e32 v3, 0xffffffc0, v3
	v_sub_u32_e32 v9, v2, v3
	v_ashrrev_i32_e32 v7, 31, v6
	v_lshlrev_b64 v[2:3], 10, v[6:7]
	v_lshlrev_b32_e32 v4, 2, v9
	v_lshl_add_u64 v[2:3], s[2:3], 0, v[2:3]
	v_ashrrev_i32_e32 v5, 31, v4
	v_lshl_add_u64 v[2:3], v[4:5], 2, v[2:3]
	global_load_dwordx4 v[186:189], v[2:3], off
	v_mul_lo_u32 v4, v6, s94
	v_lshlrev_b32_e32 v5, 3, v9
	v_add3_u32 v75, 16, v4, v5
	v_add_u32_e32 v2, 0x400, v8
	v_ashrrev_i32_e32 v3, 31, v2
	v_lshrrev_b32_e32 v3, 26, v3
	v_add_u32_e32 v3, v2, v3
	v_ashrrev_i32_e32 v6, 6, v3
	v_and_b32_e32 v3, 0xffffffc0, v3
	v_sub_u32_e32 v9, v2, v3
	v_ashrrev_i32_e32 v7, 31, v6
	v_lshlrev_b64 v[2:3], 10, v[6:7]
	v_lshlrev_b32_e32 v4, 2, v9
	v_lshl_add_u64 v[2:3], s[2:3], 0, v[2:3]
	v_ashrrev_i32_e32 v5, 31, v4
	v_lshl_add_u64 v[2:3], v[4:5], 2, v[2:3]
	global_load_dwordx4 v[190:193], v[2:3], off
	v_mul_lo_u32 v4, v6, s94
	v_lshlrev_b32_e32 v5, 3, v9
	v_add3_u32 v76, 16, v4, v5
	v_add_u32_e32 v2, 0x600, v8
	v_ashrrev_i32_e32 v3, 31, v2
	v_lshrrev_b32_e32 v3, 26, v3
	v_add_u32_e32 v3, v2, v3
	v_ashrrev_i32_e32 v6, 6, v3
	v_and_b32_e32 v3, 0xffffffc0, v3
	v_sub_u32_e32 v9, v2, v3
	v_ashrrev_i32_e32 v7, 31, v6
	v_lshlrev_b64 v[2:3], 10, v[6:7]
	v_lshlrev_b32_e32 v4, 2, v9
	v_lshl_add_u64 v[2:3], s[2:3], 0, v[2:3]
	v_ashrrev_i32_e32 v5, 31, v4
	v_lshl_add_u64 v[2:3], v[4:5], 2, v[2:3]
	global_load_dwordx4 v[204:207], v[2:3], off
	v_mul_lo_u32 v4, v6, s94
	v_lshlrev_b32_e32 v5, 3, v9
	v_add3_u32 v77, 16, v4, v5
	v_add_u32_e32 v2, 0x800, v8
	v_ashrrev_i32_e32 v3, 31, v2
	v_lshrrev_b32_e32 v3, 26, v3
	v_add_u32_e32 v3, v2, v3
	v_ashrrev_i32_e32 v6, 6, v3
	v_and_b32_e32 v3, 0xffffffc0, v3
	v_sub_u32_e32 v9, v2, v3
	v_ashrrev_i32_e32 v7, 31, v6
	v_lshlrev_b64 v[2:3], 10, v[6:7]
	v_lshlrev_b32_e32 v4, 2, v9
	v_lshl_add_u64 v[2:3], s[2:3], 0, v[2:3]
	v_ashrrev_i32_e32 v5, 31, v4
	v_lshl_add_u64 v[2:3], v[4:5], 2, v[2:3]
	global_load_dwordx4 v[208:211], v[2:3], off
	v_mul_lo_u32 v4, v6, s94
	v_lshlrev_b32_e32 v5, 3, v9
	v_add3_u32 v78, 16, v4, v5
	v_add_u32_e32 v2, 0xa00, v8
	v_ashrrev_i32_e32 v3, 31, v2
	v_lshrrev_b32_e32 v3, 26, v3
	v_add_u32_e32 v3, v2, v3
	v_ashrrev_i32_e32 v6, 6, v3
	v_and_b32_e32 v3, 0xffffffc0, v3
	v_sub_u32_e32 v9, v2, v3
	v_ashrrev_i32_e32 v7, 31, v6
	v_lshlrev_b64 v[2:3], 10, v[6:7]
	v_lshlrev_b32_e32 v4, 2, v9
	v_lshl_add_u64 v[2:3], s[2:3], 0, v[2:3]
	v_ashrrev_i32_e32 v5, 31, v4
	v_lshl_add_u64 v[2:3], v[4:5], 2, v[2:3]
	global_load_dwordx4 v[212:215], v[2:3], off
	v_mul_lo_u32 v4, v6, s94
	v_lshlrev_b32_e32 v5, 3, v9
	v_add3_u32 v79, 16, v4, v5
	v_add_u32_e32 v2, 0xc00, v8
	v_ashrrev_i32_e32 v3, 31, v2
	v_lshrrev_b32_e32 v3, 26, v3
	v_add_u32_e32 v3, v2, v3
	v_ashrrev_i32_e32 v6, 6, v3
	v_and_b32_e32 v3, 0xffffffc0, v3
	v_sub_u32_e32 v9, v2, v3
	v_ashrrev_i32_e32 v7, 31, v6
	v_lshlrev_b64 v[2:3], 10, v[6:7]
	v_lshlrev_b32_e32 v4, 2, v9
	v_lshl_add_u64 v[2:3], s[2:3], 0, v[2:3]
	v_ashrrev_i32_e32 v5, 31, v4
	v_lshl_add_u64 v[2:3], v[4:5], 2, v[2:3]
	global_load_dwordx4 v[216:219], v[2:3], off
	v_mul_lo_u32 v4, v6, s94
	v_lshlrev_b32_e32 v5, 3, v9
	v_add3_u32 v80, 16, v4, v5
	v_add_u32_e32 v2, 0xe00, v8
	v_ashrrev_i32_e32 v3, 31, v2
	v_lshrrev_b32_e32 v3, 26, v3
	v_add_u32_e32 v3, v2, v3
	v_ashrrev_i32_e32 v6, 6, v3
	v_and_b32_e32 v3, 0xffffffc0, v3
	v_sub_u32_e32 v9, v2, v3
	v_ashrrev_i32_e32 v7, 31, v6
	v_lshlrev_b64 v[2:3], 10, v[6:7]
	v_lshlrev_b32_e32 v4, 2, v9
	v_lshl_add_u64 v[2:3], s[2:3], 0, v[2:3]
	v_ashrrev_i32_e32 v5, 31, v4
	v_lshl_add_u64 v[2:3], v[4:5], 2, v[2:3]
	global_load_dwordx4 v[220:223], v[2:3], off
	v_mul_lo_u32 v4, v6, s94
	v_lshlrev_b32_e32 v5, 3, v9
	v_add3_u32 v81, 16, v4, v5
	s_waitcnt vmcnt(0)
	v_cvt_pk_bf16_f32 v182, v182, v183
	v_cvt_pk_bf16_f32 v183, v184, v185
	ds_write_b64 v74, v[182:183] offset:52480
	v_cvt_pk_bf16_f32 v186, v186, v187
	v_cvt_pk_bf16_f32 v187, v188, v189
	ds_write_b64 v75, v[186:187] offset:52480
	v_cvt_pk_bf16_f32 v190, v190, v191
	v_cvt_pk_bf16_f32 v191, v192, v193
	ds_write_b64 v76, v[190:191] offset:52480
	v_cvt_pk_bf16_f32 v204, v204, v205
	v_cvt_pk_bf16_f32 v205, v206, v207
	ds_write_b64 v77, v[204:205] offset:52480
	v_cvt_pk_bf16_f32 v208, v208, v209
	v_cvt_pk_bf16_f32 v209, v210, v211
	ds_write_b64 v78, v[208:209] offset:52480
	v_cvt_pk_bf16_f32 v212, v212, v213
	v_cvt_pk_bf16_f32 v213, v214, v215
	ds_write_b64 v79, v[212:213] offset:52480
	v_cvt_pk_bf16_f32 v216, v216, v217
	v_cvt_pk_bf16_f32 v217, v218, v219
	ds_write_b64 v80, v[216:217] offset:52480
	v_cvt_pk_bf16_f32 v220, v220, v221
	v_cvt_pk_bf16_f32 v221, v222, v223
	ds_write_b64 v81, v[220:221] offset:52480
	s_addk_i32 s11, 0x1000
	s_cmpk_eq_i32 s11, 0x2000
	s_cbranch_scc0 .LBB0_694
	v_mul_u32_u24_e32 v2, 0x210, v180
	v_add3_u32 v22, 16, v0, v2
	s_waitcnt lgkmcnt(0)
	s_barrier
; __device__ __forceinline__ float ex2(float x) { return __builtin_amdgcn_exp2f(x); }
; #define MFMA32(a, b, c) __builtin_amdgcn_mfma_f32_32x32x16_bf16((a), (b), (c), 0, 0, 0)
; template <int DQK, int DV, int MODE, int VR> ...
;     ...
; #pragma unroll
;         for (int b = 0; b < NBLK; ++b)
; #pragma unroll
;             for (int ks = 0; ks < NKS; ++ks) { const bf16x8 a = *(const bf16x8*)(lds + SP_OFF + (32 * b + r32) * SSTR + (16 * ks + 8 * hi) * 2); o[b] = MFMA32(a, qf[ks], o[b]); }
;         const float dq = ex2(a2t - a2[qb * 256 - 1]);
	ds_read_b128 v[2:5], v22 offset:52480
	ds_read_b128 v[18:21], v22 offset:52512
	s_waitcnt lgkmcnt(1)
	v_mfma_f32_32x32x16_bf16 v[2:17], v[2:5], v[138:141], 0
	v_add_u32_e32 v69, 0xcd00, v22
	s_mov_b32 s11, s87
	s_lshl_b64 s[2:3], s[10:11], 2
	s_add_u32 s2, s0, s2
	s_addc_u32 s3, s1, s3
	global_load_dword v245, v1, s[2:3] offset:-4
	s_waitcnt lgkmcnt(0)
	v_mfma_f32_32x32x16_bf16 v[2:17], v[18:21], v[82:85], v[2:17]
	ds_read_b128 v[212:215], v22 offset:52544
	ds_read_b128 v[216:219], v22 offset:52576
	ds_read_b128 v[220:223], v22 offset:52608
	s_waitcnt lgkmcnt(2)
	v_mfma_f32_32x32x16_bf16 v[2:17], v[212:215], v[86:89], v[2:17]
	ds_read_b128 v[212:215], v22 offset:52640
	s_waitcnt lgkmcnt(2)
	v_mfma_f32_32x32x16_bf16 v[2:17], v[216:219], v[90:93], v[2:17]
	ds_read_b128 v[216:219], v22 offset:52672
	s_waitcnt lgkmcnt(2)
	v_mfma_f32_32x32x16_bf16 v[2:17], v[220:223], v[94:97], v[2:17]
	ds_read_b128 v[220:223], v22 offset:52704
	s_waitcnt lgkmcnt(2)
	v_mfma_f32_32x32x16_bf16 v[2:17], v[212:215], v[98:101], v[2:17]
	ds_read_b128 v[212:215], v22 offset:52736
	s_waitcnt lgkmcnt(2)
	v_mfma_f32_32x32x16_bf16 v[2:17], v[216:219], v[102:105], v[2:17]
	ds_read_b128 v[216:219], v22 offset:52768
	s_waitcnt lgkmcnt(2)
	v_mfma_f32_32x32x16_bf16 v[2:17], v[220:223], v[106:109], v[2:17]
	ds_read_b128 v[220:223], v22 offset:52800
	s_waitcnt lgkmcnt(2)
	v_mfma_f32_32x32x16_bf16 v[2:17], v[212:215], v[110:113], v[2:17]
	ds_read_b128 v[212:215], v22 offset:52832
	s_waitcnt lgkmcnt(2)
	v_mfma_f32_32x32x16_bf16 v[2:17], v[216:219], v[114:117], v[2:17]
	ds_read_b128 v[216:219], v22 offset:52864
	s_waitcnt lgkmcnt(2)
	v_mfma_f32_32x32x16_bf16 v[2:17], v[220:223], v[118:121], v[2:17]
	ds_read_b128 v[220:223], v22 offset:52896
	s_waitcnt lgkmcnt(2)
	v_mfma_f32_32x32x16_bf16 v[2:17], v[212:215], v[122:125], v[2:17]
	ds_read_b128 v[212:215], v22 offset:52928
	s_waitcnt lgkmcnt(2)
	v_mfma_f32_32x32x16_bf16 v[2:17], v[216:219], v[126:129], v[2:17]
	ds_read_b128 v[216:219], v22 offset:52960
	s_waitcnt lgkmcnt(2)
	v_mfma_f32_32x32x16_bf16 v[2:17], v[220:223], v[130:133], v[2:17]
	s_waitcnt lgkmcnt(1)
	v_mfma_f32_32x32x16_bf16 v[2:17], v[212:215], v[134:137], v[2:17]
	s_waitcnt lgkmcnt(0)
	v_mfma_f32_32x32x16_bf16 v[2:17], v[216:219], v[142:145], v[2:17]
	ds_read_b128 v[18:21], v69 offset:16896
	ds_read_b128 v[34:37], v69 offset:16928
	ds_read_b128 v[50:53], v69 offset:33824
	ds_read_b128 v[70:73], v69 offset:50720
	s_waitcnt lgkmcnt(3)
	v_mfma_f32_32x32x16_bf16 v[18:33], v[18:21], v[138:141], 0
	s_waitcnt lgkmcnt(2)
	v_mfma_f32_32x32x16_bf16 v[18:33], v[34:37], v[82:85], v[18:33]
	ds_read_b128 v[212:215], v69 offset:16960
	ds_read_b128 v[216:219], v69 offset:16992
	ds_read_b128 v[220:223], v69 offset:17024
	s_waitcnt lgkmcnt(2)
	v_mfma_f32_32x32x16_bf16 v[18:33], v[212:215], v[86:89], v[18:33]
	ds_read_b128 v[212:215], v69 offset:17056
	s_waitcnt lgkmcnt(2)
	v_mfma_f32_32x32x16_bf16 v[18:33], v[216:219], v[90:93], v[18:33]
	ds_read_b128 v[216:219], v69 offset:17088
	s_waitcnt lgkmcnt(2)
	v_mfma_f32_32x32x16_bf16 v[18:33], v[220:223], v[94:97], v[18:33]
	ds_read_b128 v[220:223], v69 offset:17120
	s_waitcnt lgkmcnt(2)
	v_mfma_f32_32x32x16_bf16 v[18:33], v[212:215], v[98:101], v[18:33]
	ds_read_b128 v[212:215], v69 offset:17152
	s_waitcnt lgkmcnt(2)
	v_mfma_f32_32x32x16_bf16 v[18:33], v[216:219], v[102:105], v[18:33]
	ds_read_b128 v[216:219], v69 offset:17184
	s_waitcnt lgkmcnt(2)
	v_mfma_f32_32x32x16_bf16 v[18:33], v[220:223], v[106:109], v[18:33]
	ds_read_b128 v[220:223], v69 offset:17216
	s_waitcnt lgkmcnt(2)
	v_mfma_f32_32x32x16_bf16 v[18:33], v[212:215], v[110:113], v[18:33]
	ds_read_b128 v[212:215], v69 offset:17248
	s_waitcnt lgkmcnt(2)
	v_mfma_f32_32x32x16_bf16 v[18:33], v[216:219], v[114:117], v[18:33]
	ds_read_b128 v[216:219], v69 offset:17280
	s_waitcnt lgkmcnt(2)
	v_mfma_f32_32x32x16_bf16 v[18:33], v[220:223], v[118:121], v[18:33]
	ds_read_b128 v[220:223], v69 offset:17312
	s_waitcnt lgkmcnt(2)
	v_mfma_f32_32x32x16_bf16 v[18:33], v[212:215], v[122:125], v[18:33]
	ds_read_b128 v[212:215], v69 offset:17344
	s_waitcnt lgkmcnt(2)
	v_mfma_f32_32x32x16_bf16 v[18:33], v[216:219], v[126:129], v[18:33]
	ds_read_b128 v[216:219], v69 offset:17376
	s_waitcnt lgkmcnt(2)
	v_mfma_f32_32x32x16_bf16 v[18:33], v[220:223], v[130:133], v[18:33]
	ds_read_b128 v[220:223], v69 offset:33792
	s_waitcnt lgkmcnt(2)
	v_mfma_f32_32x32x16_bf16 v[18:33], v[212:215], v[134:137], v[18:33]
	s_waitcnt lgkmcnt(1)
	v_mfma_f32_32x32x16_bf16 v[18:33], v[216:219], v[142:145], v[18:33]
	s_waitcnt lgkmcnt(0)
	v_mfma_f32_32x32x16_bf16 v[34:49], v[220:223], v[138:141], 0
	v_mfma_f32_32x32x16_bf16 v[34:49], v[50:53], v[82:85], v[34:49]
	ds_read_b128 v[212:215], v69 offset:33856
	ds_read_b128 v[216:219], v69 offset:33888
	ds_read_b128 v[220:223], v69 offset:33920
	s_waitcnt lgkmcnt(2)
	v_mfma_f32_32x32x16_bf16 v[34:49], v[212:215], v[86:89], v[34:49]
	ds_read_b128 v[212:215], v69 offset:33952
	s_waitcnt lgkmcnt(2)
	v_mfma_f32_32x32x16_bf16 v[34:49], v[216:219], v[90:93], v[34:49]
	ds_read_b128 v[216:219], v69 offset:33984
	s_waitcnt lgkmcnt(2)
	v_mfma_f32_32x32x16_bf16 v[34:49], v[220:223], v[94:97], v[34:49]
	ds_read_b128 v[220:223], v69 offset:34016
	s_waitcnt lgkmcnt(2)
	v_mfma_f32_32x32x16_bf16 v[34:49], v[212:215], v[98:101], v[34:49]
	ds_read_b128 v[212:215], v69 offset:34048
	s_waitcnt lgkmcnt(2)
; __device__ __forceinline__ float ex2(float x) { return __builtin_amdgcn_exp2f(x); }
; #define MFMA32(a, b, c) __builtin_amdgcn_mfma_f32_32x32x16_bf16((a), (b), (c), 0, 0, 0)
; template <int DQK, int DV, int MODE, int VR> ...
;     ...
; #pragma unroll
;         for (int b = 0; b < NBLK; ++b)
; #pragma unroll
;             for (int ks = 0; ks < NKS; ++ks) { const bf16x8 a = *(const bf16x8*)(lds + SP_OFF + (32 * b + r32) * SSTR + (16 * ks + 8 * hi) * 2); o[b] = MFMA32(a, qf[ks], o[b]); }
;         const float dq = ex2(a2t - a2[qb * 256 - 1]);
; #pragma unroll
;         for (int b = 0; b < NBLK; ++b)
; #pragma unroll
;             for (int r = 0; r < 16; ++r) o[b][r] *= dq;
	v_mfma_f32_32x32x16_bf16 v[34:49], v[216:219], v[102:105], v[34:49]
	ds_read_b128 v[216:219], v69 offset:34080
	s_waitcnt lgkmcnt(2)
	v_mfma_f32_32x32x16_bf16 v[34:49], v[220:223], v[106:109], v[34:49]
	ds_read_b128 v[220:223], v69 offset:34112
	s_waitcnt lgkmcnt(2)
	v_mfma_f32_32x32x16_bf16 v[34:49], v[212:215], v[110:113], v[34:49]
	ds_read_b128 v[212:215], v69 offset:34144
	s_waitcnt lgkmcnt(2)
	v_mfma_f32_32x32x16_bf16 v[34:49], v[216:219], v[114:117], v[34:49]
	ds_read_b128 v[216:219], v69 offset:34176
	s_waitcnt lgkmcnt(2)
	v_mfma_f32_32x32x16_bf16 v[34:49], v[220:223], v[118:121], v[34:49]
	ds_read_b128 v[220:223], v69 offset:34208
	s_waitcnt lgkmcnt(2)
	v_mfma_f32_32x32x16_bf16 v[34:49], v[212:215], v[122:125], v[34:49]
	ds_read_b128 v[212:215], v69 offset:34240
	s_waitcnt lgkmcnt(2)
	v_mfma_f32_32x32x16_bf16 v[34:49], v[216:219], v[126:129], v[34:49]
	ds_read_b128 v[216:219], v69 offset:34272
	s_waitcnt lgkmcnt(2)
	v_mfma_f32_32x32x16_bf16 v[34:49], v[220:223], v[130:133], v[34:49]
	ds_read_b128 v[220:223], v69 offset:50688
	s_waitcnt lgkmcnt(2)
	v_mfma_f32_32x32x16_bf16 v[34:49], v[212:215], v[134:137], v[34:49]
	s_waitcnt lgkmcnt(1)
	v_mfma_f32_32x32x16_bf16 v[34:49], v[216:219], v[142:145], v[34:49]
	s_waitcnt lgkmcnt(0)
	v_mfma_f32_32x32x16_bf16 v[50:65], v[220:223], v[138:141], 0
	v_mfma_f32_32x32x16_bf16 v[50:65], v[70:73], v[82:85], v[50:65]
	ds_read_b128 v[212:215], v69 offset:50752
	ds_read_b128 v[216:219], v69 offset:50784
	ds_read_b128 v[220:223], v69 offset:50816
	s_waitcnt lgkmcnt(2)
	v_mfma_f32_32x32x16_bf16 v[50:65], v[212:215], v[86:89], v[50:65]
	ds_read_b128 v[212:215], v69 offset:50848
	s_waitcnt lgkmcnt(2)
	v_mfma_f32_32x32x16_bf16 v[50:65], v[216:219], v[90:93], v[50:65]
	ds_read_b128 v[216:219], v69 offset:50880
	s_waitcnt lgkmcnt(2)
	v_mfma_f32_32x32x16_bf16 v[50:65], v[220:223], v[94:97], v[50:65]
	ds_read_b128 v[220:223], v69 offset:50912
	s_waitcnt lgkmcnt(2)
	v_mfma_f32_32x32x16_bf16 v[50:65], v[212:215], v[98:101], v[50:65]
	ds_read_b128 v[212:215], v69 offset:50944
	s_waitcnt lgkmcnt(2)
	v_mfma_f32_32x32x16_bf16 v[50:65], v[216:219], v[102:105], v[50:65]
	ds_read_b128 v[216:219], v69 offset:50976
	s_waitcnt lgkmcnt(2)
	v_mfma_f32_32x32x16_bf16 v[50:65], v[220:223], v[106:109], v[50:65]
	ds_read_b128 v[220:223], v69 offset:51008
	s_waitcnt lgkmcnt(2)
	v_mfma_f32_32x32x16_bf16 v[50:65], v[212:215], v[110:113], v[50:65]
	ds_read_b128 v[212:215], v69 offset:51040
	s_waitcnt lgkmcnt(2)
	v_mfma_f32_32x32x16_bf16 v[50:65], v[216:219], v[114:117], v[50:65]
	ds_read_b128 v[216:219], v69 offset:51072
	s_waitcnt lgkmcnt(2)
	v_mfma_f32_32x32x16_bf16 v[50:65], v[220:223], v[118:121], v[50:65]
	ds_read_b128 v[220:223], v69 offset:51104
	s_waitcnt lgkmcnt(2)
	v_mfma_f32_32x32x16_bf16 v[50:65], v[212:215], v[122:125], v[50:65]
	ds_read_b128 v[212:215], v69 offset:51136
	s_waitcnt lgkmcnt(2)
	v_mfma_f32_32x32x16_bf16 v[50:65], v[216:219], v[126:129], v[50:65]
	ds_read_b128 v[216:219], v69 offset:51168
	s_waitcnt lgkmcnt(2)
	v_mfma_f32_32x32x16_bf16 v[50:65], v[220:223], v[130:133], v[50:65]
	s_waitcnt lgkmcnt(1)
	v_mfma_f32_32x32x16_bf16 v[50:65], v[212:215], v[134:137], v[50:65]
	s_waitcnt vmcnt(0)
	v_sub_f32_e32 v69, v175, v245
	s_waitcnt lgkmcnt(0)
	v_mfma_f32_32x32x16_bf16 v[50:65], v[216:219], v[142:145], v[50:65]
	v_exp_f32_e32 v70, v69
	s_nop 0
	v_pk_mul_f32 v[16:17], v[16:17], v[70:71] op_sel_hi:[1,0]
	v_pk_mul_f32 v[14:15], v[14:15], v[70:71] op_sel_hi:[1,0]
	v_pk_mul_f32 v[12:13], v[12:13], v[70:71] op_sel_hi:[1,0]
	v_pk_mul_f32 v[10:11], v[10:11], v[70:71] op_sel_hi:[1,0]
	v_pk_mul_f32 v[8:9], v[8:9], v[70:71] op_sel_hi:[1,0]
	v_pk_mul_f32 v[6:7], v[6:7], v[70:71] op_sel_hi:[1,0]
	v_pk_mul_f32 v[4:5], v[4:5], v[70:71] op_sel_hi:[1,0]
	v_pk_mul_f32 v[2:3], v[2:3], v[70:71] op_sel_hi:[1,0]
	v_pk_mul_f32 v[32:33], v[32:33], v[70:71] op_sel_hi:[1,0]
	v_pk_mul_f32 v[30:31], v[30:31], v[70:71] op_sel_hi:[1,0]
	v_pk_mul_f32 v[28:29], v[28:29], v[70:71] op_sel_hi:[1,0]
	v_pk_mul_f32 v[26:27], v[26:27], v[70:71] op_sel_hi:[1,0]
	v_pk_mul_f32 v[24:25], v[24:25], v[70:71] op_sel_hi:[1,0]
	v_pk_mul_f32 v[22:23], v[22:23], v[70:71] op_sel_hi:[1,0]
	v_pk_mul_f32 v[20:21], v[20:21], v[70:71] op_sel_hi:[1,0]
	v_pk_mul_f32 v[18:19], v[18:19], v[70:71] op_sel_hi:[1,0]
	v_pk_mul_f32 v[48:49], v[48:49], v[70:71] op_sel_hi:[1,0]
	v_pk_mul_f32 v[46:47], v[46:47], v[70:71] op_sel_hi:[1,0]
	v_pk_mul_f32 v[44:45], v[44:45], v[70:71] op_sel_hi:[1,0]
	v_pk_mul_f32 v[42:43], v[42:43], v[70:71] op_sel_hi:[1,0]
	v_pk_mul_f32 v[40:41], v[40:41], v[70:71] op_sel_hi:[1,0]
	v_pk_mul_f32 v[38:39], v[38:39], v[70:71] op_sel_hi:[1,0]
	v_pk_mul_f32 v[36:37], v[36:37], v[70:71] op_sel_hi:[1,0]
	v_pk_mul_f32 v[34:35], v[34:35], v[70:71] op_sel_hi:[1,0]
	v_pk_mul_f32 v[64:65], v[64:65], v[70:71] op_sel_hi:[1,0]
	v_pk_mul_f32 v[62:63], v[62:63], v[70:71] op_sel_hi:[1,0]
	v_pk_mul_f32 v[60:61], v[60:61], v[70:71] op_sel_hi:[1,0]
	v_pk_mul_f32 v[58:59], v[58:59], v[70:71] op_sel_hi:[1,0]
	v_pk_mul_f32 v[56:57], v[56:57], v[70:71] op_sel_hi:[1,0]
	v_pk_mul_f32 v[54:55], v[54:55], v[70:71] op_sel_hi:[1,0]
	v_pk_mul_f32 v[52:53], v[52:53], v[70:71] op_sel_hi:[1,0]
	v_pk_mul_f32 v[50:51], v[50:51], v[70:71] op_sel_hi:[1,0]
	s_branch .LBB0_750
